# phase-5 row-norm wave map rotated by 64 blocks so the waves with a fifth trip no longer sit on the 7-chunk LRU blocks, on top of v30
# speedup vs baseline: 1.0017x; 1.0017x over previous
; __device__ __forceinline__ void mixprep_rows(ArgP a, int l, int gw, int NGW, int lane) {
;     const bf16_t* Z = (const bf16_t*)(a->ws + OFF_Z);
;     const float* qn = a->in[19] + l * 256; const float* kvn = a->in[21] + l * 128; const float* nqg = a->in[25] + l * 64; const float* nkg = a->in[26] + l * 64;
;     const float nscale = 0.125f * LOG2E;
;     const f32x4 gq = *(const f32x4*)(qn + 4 * lane); const float gkv0 = kvn[2 * lane], gkv1 = kvn[2 * lane + 1];
;     const int hd = lane >> 4, d0 = 4 * (lane & 15);
;     const f32x4 gnq = *(const f32x4*)(nqg + d0), gnk = *(const f32x4*)(nkg + d0);
;     for (int row0 = gw * 4; row0 < MTOT; row0 += NGW * 4) {
;         u32x2 ucq[4], unq[4], unk[4]; unsigned uckv[4];
; #pragma unroll
;         for (int t4 = 0; t4 < 4; ++t4) { const bf16_t* zr = Z + (size_t)(row0 + t4) * INW;
;             ucq[t4] = *(const u32x2*)(zr + Z_CQ + 4 * lane); uckv[t4] = *(const unsigned*)(zr + Z_CKV + 2 * lane);
;             unq[t4] = *(const u32x2*)(zr + Z_NQ + 4 * lane); unk[t4] = *(const u32x2*)(zr + Z_NK + 4 * lane); }
.LBB0_765:
	s_cmp_gt_i32 s87, 4
	s_mov_b64 s[0:1], -1
	s_cbranch_scc0 .LBB0_952
	v_mbcnt_lo_u32_b32 v14, -1, 0
	v_mbcnt_hi_u32_b32 v14, -1, v14
	s_cmpk_gt_i32 s91, 0x20ff
	v_lshlrev_b32_e32 v16, 2, v14
	v_ashrrev_i32_e32 v17, 31, v16
	v_lshlrev_b64 v[18:19], 1, v[16:17]
	s_cbranch_scc1 .LBB0_769
	s_lshl_b32 s0, s62, 7
	s_ashr_i32 s1, s0, 31
	s_lshl_b64 s[12:13], s[0:1], 2
	s_load_dwordx2 s[14:15], s[30:31], 0x98
	s_load_dwordx2 s[20:21], s[30:31], 0xa8
	s_load_dwordx4 s[0:3], s[30:31], 0xc8
	v_lshlrev_b32_e32 v26, 1, v14
	v_ashrrev_i32_e32 v27, 31, v26
	v_and_b32_e32 v15, 60, v16
	s_waitcnt lgkmcnt(0)
	s_add_u32 s12, s20, s12
	s_addc_u32 s13, s21, s13
	v_lshl_add_u64 v[2:3], v[26:27], 2, s[12:13]
	s_lshl_b32 s12, s62, 6
	s_ashr_i32 s13, s12, 31
	s_add_i32 s40, s91, 0x200
	s_and_b32 s40, s40, 0x7ff
	s_cmpk_lg_i32 s90, 0x100
	s_cselect_b32 s40, s91, s40
	s_lshl_b32 s40, s40, 2
	s_lshl_b64 s[12:13], s[12:13], 2
	s_add_u32 s2, s2, s12
	s_addc_u32 s3, s3, s13
	s_add_u32 s0, s0, s12
	v_lshlrev_b32_e32 v6, 2, v15
	s_addc_u32 s1, s1, s13
	global_load_dwordx2 v[20:21], v[2:3], off
	v_lshlrev_b32_e32 v22, 1, v15
	global_load_dwordx4 v[2:5], v6, s[2:3]
	v_mov_b32_e32 v23, v0
	global_load_dwordx4 v[6:9], v6, s[0:1]
	s_lshl_b32 s0, s62, 8
	s_ashr_i32 s1, s0, 31
	s_lshl_b64 s[0:1], s[0:1], 2
	s_add_u32 s0, s14, s0
	s_addc_u32 s1, s15, s1
	v_lshl_add_u64 v[10:11], v[16:17], 2, s[0:1]
	global_load_dwordx4 v[10:13], v[10:11], off
	v_lshl_add_u64 v[24:25], s[10:11], 0, v[22:23]
	s_mov_b64 s[0:1], 0x1d670000
	v_lshl_add_u64 v[22:23], v[24:25], 0, s[0:1]
	s_mov_b64 s[0:1], 0x1e6f0000
	v_ashrrev_i32_e32 v15, 31, v14
	s_ashr_i32 s41, s40, 31
	v_lshl_add_u64 v[24:25], v[24:25], 0, s[0:1]
	v_lshlrev_b64 v[32:33], 2, v[14:15]
	s_lshl_b64 s[0:1], s[40:41], 9
	v_mov_b32_e32 v15, 0xf40
	s_lshl_b32 s42, s90, 5
	v_lshl_add_u64 v[26:27], v[26:27], 1, s[0:1]
	v_lshl_add_u64 v[28:29], s[0:1], 0, v[18:19]
	v_mad_i64_i32 v[30:31], s[0:1], s40, v15, v[18:19]
	s_ashr_i32 s43, s42, 31
	v_sub_co_u32_e32 v32, vcc, v30, v32
	v_ashrrev_i32_e32 v1, 4, v14
	s_lshl_b64 s[46:47], s[42:43], 9
	s_mul_i32 s48, s90, 0x1e800
	s_mul_hi_i32 s49, s42, 0xf40
	v_subb_co_u32_e32 v33, vcc, v31, v33, vcc
